# phase B epilogue: sigmoid tiles take a 4-op out-of-line path, silu path loses its v_cndmask
# baseline (speedup 1.0000x reference)
; __device__ __forceinline__ unsigned cvt_pk_bf16(float lo, float hi) { unsigned r; asm volatile("v_cvt_pk_bf16_f32 %0, %1, %2" : "=v"(r) : "v"(lo), "v"(hi)); return r; }
; __device__ __forceinline__ float sigmoidf_(float x) { return __builtin_amdgcn_rcpf(1.0f + __builtin_amdgcn_exp2f(-1.4426950408889634f * x)); }
;     __device__ __forceinline__ bool operator()(f32x4 (&acc)[2][2][4][2], const Unit& u, int wr, int wc, int fr, int fq) const {
;     ...
;             for (int m = 0; m < 4; ++m) { bf16_t* rowp = Z + (size_t)(row0 + ai * HALF + m * 16) * NZ + col0;
; #pragma unroll
;                 for (int bj = 0; bj < 2; ++bj) { f32x4 v0 = acc[ai][bj][m][0], v1 = acc[ai][bj][m][1];
;                     if (kind) {
; #pragma unroll
;                         for (int j = 0; j < 4; ++j) { const float s0 = sigmoidf_(v0[j]), s1 = sigmoidf_(v1[j]); v0[j] = kind == 1 ? v0[j] * s0 : s0; v1[j] = kind == 1 ? v1[j] * s1 : s1; } }
;                     u32x4 w; w.x = cvt_pk_bf16(v0[0], v0[1]); w.y = cvt_pk_bf16(v0[2], v0[3]); w.z = cvt_pk_bf16(v1[0], v1[1]); w.w = cvt_pk_bf16(v1[2], v1[3]);
;                     *(u32x4*)(rowp + bj * HALF) = w; } }
.LBB0_298:
	s_cmp_lg_u32 s8, 0
	s_cselect_b64 s[26:27], -1, 0
	s_cmp_eq_u32 s8, 2
	s_cselect_b64 s[6:7], -1, 0
	s_cmp_eq_u32 s8, 0
	s_cbranch_scc1 .LBB0_300
	s_and_b64 vcc, exec, s[6:7]
	s_cbranch_vccnz .Lsg_0
	v_mul_f32_e32 v142, 0xbfb8aa3b, v128
	v_mul_f32_e32 v143, 0xbfb8aa3b, v124
	v_exp_f32_e32 v142, v142
	v_exp_f32_e32 v143, v143
	v_add_f32_e32 v142, 1.0, v142
	v_add_f32_e32 v143, 1.0, v143
	v_rcp_f32_e32 v142, v142
	v_rcp_f32_e32 v143, v143
	v_mul_f32_e32 v128, v128, v142
	v_mul_f32_e32 v124, v124, v143
	v_mul_f32_e32 v142, 0xbfb8aa3b, v129
	v_mul_f32_e32 v143, 0xbfb8aa3b, v125
	v_exp_f32_e32 v142, v142
	v_exp_f32_e32 v143, v143
	v_add_f32_e32 v142, 1.0, v142
	v_add_f32_e32 v143, 1.0, v143
	v_rcp_f32_e32 v142, v142
	v_rcp_f32_e32 v143, v143
	v_mul_f32_e32 v129, v129, v142
	v_mul_f32_e32 v125, v125, v143
	v_mul_f32_e32 v142, 0xbfb8aa3b, v130
	v_mul_f32_e32 v143, 0xbfb8aa3b, v126
	v_exp_f32_e32 v142, v142
	v_exp_f32_e32 v143, v143
	v_add_f32_e32 v142, 1.0, v142
	v_add_f32_e32 v143, 1.0, v143
	v_rcp_f32_e32 v142, v142
	v_rcp_f32_e32 v143, v143
	v_mul_f32_e32 v130, v130, v142
	v_mul_f32_e32 v126, v126, v143
	v_mul_f32_e32 v142, 0xbfb8aa3b, v131
	v_mul_f32_e32 v143, 0xbfb8aa3b, v127
	v_exp_f32_e32 v142, v142
	v_exp_f32_e32 v143, v143
	v_add_f32_e32 v142, 1.0, v142
	v_add_f32_e32 v143, 1.0, v143
	v_rcp_f32_e32 v142, v142
	v_rcp_f32_e32 v143, v143
	v_mul_f32_e32 v131, v131, v142
	v_mul_f32_e32 v127, v127, v143
.LBB0_300:
	v_add_u32_e32 v150, s43, v146
	v_add_u32_e32 v142, s52, v148
	v_mov_b64_e32 v[144:145], s[18:19]
	v_ashrrev_i32_e32 v143, 31, v142
	v_mad_i64_i32 v[144:145], s[8:9], v150, s42, v[144:145]
	v_cvt_pk_bf16_f32 v128, v128, v129
	v_cvt_pk_bf16_f32 v129, v130, v131
	v_cvt_pk_bf16_f32 v130, v124, v125
	v_cndmask_b32_e64 v124, 0, 1, s[26:27]
	v_lshl_add_u64 v[144:145], v[142:143], 1, v[144:145]
	v_cmp_ne_u32_e64 s[8:9], 1, v124
	s_andn2_b64 vcc, exec, s[26:27]
	v_cvt_pk_bf16_f32 v131, v126, v127
	global_store_dwordx4 v[144:145], v[128:131], off
	s_cbranch_vccnz .LBB0_302
	s_and_b64 vcc, exec, s[6:7]
	s_cbranch_vccnz .Lsg_1
	v_mul_f32_e32 v124, 0xbfb8aa3b, v120
	v_mul_f32_e32 v125, 0xbfb8aa3b, v116
	v_exp_f32_e32 v124, v124
	v_exp_f32_e32 v125, v125
	v_add_f32_e32 v124, 1.0, v124
	v_add_f32_e32 v125, 1.0, v125
	v_rcp_f32_e32 v124, v124
	v_rcp_f32_e32 v125, v125
	v_mul_f32_e32 v120, v120, v124
	v_mul_f32_e32 v116, v116, v125
	v_mul_f32_e32 v124, 0xbfb8aa3b, v121
	v_mul_f32_e32 v125, 0xbfb8aa3b, v117
	v_exp_f32_e32 v124, v124
	v_exp_f32_e32 v125, v125
	v_add_f32_e32 v124, 1.0, v124
	v_add_f32_e32 v125, 1.0, v125
	v_rcp_f32_e32 v124, v124
	v_rcp_f32_e32 v125, v125
	v_mul_f32_e32 v121, v121, v124
	v_mul_f32_e32 v117, v117, v125
	v_mul_f32_e32 v124, 0xbfb8aa3b, v122
	v_mul_f32_e32 v125, 0xbfb8aa3b, v118
	v_exp_f32_e32 v124, v124
	v_exp_f32_e32 v125, v125
	v_add_f32_e32 v124, 1.0, v124
	v_add_f32_e32 v125, 1.0, v125
	v_rcp_f32_e32 v124, v124
	v_rcp_f32_e32 v125, v125
	v_mul_f32_e32 v122, v122, v124
	v_mul_f32_e32 v118, v118, v125
	v_mul_f32_e32 v124, 0xbfb8aa3b, v123
	v_mul_f32_e32 v125, 0xbfb8aa3b, v119
	v_exp_f32_e32 v124, v124
	v_exp_f32_e32 v125, v125
	v_add_f32_e32 v124, 1.0, v124
	v_add_f32_e32 v125, 1.0, v125
	v_rcp_f32_e32 v124, v124
	v_rcp_f32_e32 v125, v125
	v_mul_f32_e32 v123, v123, v124
	v_mul_f32_e32 v119, v119, v125
.LBB0_302:
	s_and_b64 vcc, exec, s[8:9]
	v_cvt_pk_bf16_f32 v120, v120, v121
	v_cvt_pk_bf16_f32 v121, v122, v123
	v_cvt_pk_bf16_f32 v122, v116, v117
	v_cvt_pk_bf16_f32 v123, v118, v119
	global_store_dwordx4 v[144:145], v[120:123], off offset:256
	s_cbranch_vccnz .LBB0_304
	s_and_b64 vcc, exec, s[6:7]
	s_cbranch_vccnz .Lsg_2
	v_mul_f32_e32 v116, 0xbfb8aa3b, v110
	v_mul_f32_e32 v117, 0xbfb8aa3b, v106
	v_exp_f32_e32 v116, v116
	v_exp_f32_e32 v117, v117
	v_add_f32_e32 v116, 1.0, v116
	v_add_f32_e32 v117, 1.0, v117
	v_rcp_f32_e32 v116, v116
	v_rcp_f32_e32 v117, v117
	v_mul_f32_e32 v110, v110, v116
	v_mul_f32_e32 v106, v106, v117
	v_mul_f32_e32 v116, 0xbfb8aa3b, v111
	v_mul_f32_e32 v117, 0xbfb8aa3b, v107
	v_exp_f32_e32 v116, v116
	v_exp_f32_e32 v117, v117
	v_add_f32_e32 v116, 1.0, v116
	v_add_f32_e32 v117, 1.0, v117
	v_rcp_f32_e32 v116, v116
	v_rcp_f32_e32 v117, v117
	v_mul_f32_e32 v111, v111, v116
	v_mul_f32_e32 v107, v107, v117
	v_mul_f32_e32 v116, 0xbfb8aa3b, v112
	v_mul_f32_e32 v117, 0xbfb8aa3b, v108
	v_exp_f32_e32 v116, v116
	v_exp_f32_e32 v117, v117
	v_add_f32_e32 v116, 1.0, v116
	v_add_f32_e32 v117, 1.0, v117
	v_rcp_f32_e32 v116, v116
	v_rcp_f32_e32 v117, v117
	v_mul_f32_e32 v112, v112, v116
	v_mul_f32_e32 v108, v108, v117
	v_mul_f32_e32 v116, 0xbfb8aa3b, v113
	v_mul_f32_e32 v117, 0xbfb8aa3b, v109
	v_exp_f32_e32 v116, v116
	v_exp_f32_e32 v117, v117
	v_add_f32_e32 v116, 1.0, v116
	v_add_f32_e32 v117, 1.0, v117
	v_rcp_f32_e32 v116, v116
	v_rcp_f32_e32 v117, v117
	v_mul_f32_e32 v113, v113, v116
	v_mul_f32_e32 v109, v109, v117
; __device__ __forceinline__ unsigned cvt_pk_bf16(float lo, float hi) { unsigned r; asm volatile("v_cvt_pk_bf16_f32 %0, %1, %2" : "=v"(r) : "v"(lo), "v"(hi)); return r; }
; __device__ __forceinline__ float sigmoidf_(float x) { return __builtin_amdgcn_rcpf(1.0f + __builtin_amdgcn_exp2f(-1.4426950408889634f * x)); }
;     __device__ __forceinline__ bool operator()(f32x4 (&acc)[2][2][4][2], const Unit& u, int wr, int wc, int fr, int fq) const {
;     ...
;             for (int m = 0; m < 4; ++m) { bf16_t* rowp = Z + (size_t)(row0 + ai * HALF + m * 16) * NZ + col0;
; #pragma unroll
;                 for (int bj = 0; bj < 2; ++bj) { f32x4 v0 = acc[ai][bj][m][0], v1 = acc[ai][bj][m][1];
;                     if (kind) {
; #pragma unroll
;                         for (int j = 0; j < 4; ++j) { const float s0 = sigmoidf_(v0[j]), s1 = sigmoidf_(v1[j]); v0[j] = kind == 1 ? v0[j] * s0 : s0; v1[j] = kind == 1 ? v1[j] * s1 : s1; } }
;                     u32x4 w; w.x = cvt_pk_bf16(v0[0], v0[1]); w.y = cvt_pk_bf16(v0[2], v0[3]); w.z = cvt_pk_bf16(v1[0], v1[1]); w.w = cvt_pk_bf16(v1[2], v1[3]);
;                     *(u32x4*)(rowp + bj * HALF) = w; } }
.LBB0_304:
	v_add_u32_e32 v118, 16, v150
	v_mov_b64_e32 v[116:117], s[18:19]
	v_mad_i64_i32 v[116:117], s[26:27], v118, s42, v[116:117]
	v_lshl_add_u64 v[116:117], v[142:143], 1, v[116:117]
	s_and_b64 vcc, exec, s[8:9]
	v_cvt_pk_bf16_f32 v110, v110, v111
	v_cvt_pk_bf16_f32 v111, v112, v113
	v_cvt_pk_bf16_f32 v112, v106, v107
	v_cvt_pk_bf16_f32 v113, v108, v109
	global_store_dwordx4 v[116:117], v[110:113], off
	s_cbranch_vccnz .LBB0_306
	s_and_b64 vcc, exec, s[6:7]
	s_cbranch_vccnz .Lsg_3
	v_mul_f32_e32 v106, 0xbfb8aa3b, v102
	v_mul_f32_e32 v107, 0xbfb8aa3b, v98
	v_exp_f32_e32 v106, v106
	v_exp_f32_e32 v107, v107
	v_add_f32_e32 v106, 1.0, v106
	v_add_f32_e32 v107, 1.0, v107
	v_rcp_f32_e32 v106, v106
	v_rcp_f32_e32 v107, v107
	v_mul_f32_e32 v102, v102, v106
	v_mul_f32_e32 v98, v98, v107
	v_mul_f32_e32 v106, 0xbfb8aa3b, v103
	v_mul_f32_e32 v107, 0xbfb8aa3b, v99
	v_exp_f32_e32 v106, v106
	v_exp_f32_e32 v107, v107
	v_add_f32_e32 v106, 1.0, v106
	v_add_f32_e32 v107, 1.0, v107
	v_rcp_f32_e32 v106, v106
	v_rcp_f32_e32 v107, v107
	v_mul_f32_e32 v103, v103, v106
	v_mul_f32_e32 v99, v99, v107
	v_mul_f32_e32 v106, 0xbfb8aa3b, v104
	v_mul_f32_e32 v107, 0xbfb8aa3b, v100
	v_exp_f32_e32 v106, v106
	v_exp_f32_e32 v107, v107
	v_add_f32_e32 v106, 1.0, v106
	v_add_f32_e32 v107, 1.0, v107
	v_rcp_f32_e32 v106, v106
	v_rcp_f32_e32 v107, v107
	v_mul_f32_e32 v104, v104, v106
	v_mul_f32_e32 v100, v100, v107
	v_mul_f32_e32 v106, 0xbfb8aa3b, v105
	v_mul_f32_e32 v107, 0xbfb8aa3b, v101
	v_exp_f32_e32 v106, v106
	v_exp_f32_e32 v107, v107
	v_add_f32_e32 v106, 1.0, v106
	v_add_f32_e32 v107, 1.0, v107
	v_rcp_f32_e32 v106, v106
	v_rcp_f32_e32 v107, v107
	v_mul_f32_e32 v105, v105, v106
	v_mul_f32_e32 v101, v101, v107
.LBB0_306:
	s_and_b64 vcc, exec, s[8:9]
	v_cvt_pk_bf16_f32 v102, v102, v103
	v_cvt_pk_bf16_f32 v103, v104, v105
	v_cvt_pk_bf16_f32 v104, v98, v99
	v_cvt_pk_bf16_f32 v105, v100, v101
	global_store_dwordx4 v[116:117], v[102:105], off offset:256
	s_cbranch_vccnz .LBB0_308
	s_and_b64 vcc, exec, s[6:7]
	s_cbranch_vccnz .Lsg_4
	v_mul_f32_e32 v98, 0xbfb8aa3b, v94
	v_mul_f32_e32 v99, 0xbfb8aa3b, v90
	v_exp_f32_e32 v98, v98
	v_exp_f32_e32 v99, v99
	v_add_f32_e32 v98, 1.0, v98
	v_add_f32_e32 v99, 1.0, v99
	v_rcp_f32_e32 v98, v98
	v_rcp_f32_e32 v99, v99
	v_mul_f32_e32 v94, v94, v98
	v_mul_f32_e32 v90, v90, v99
	v_mul_f32_e32 v98, 0xbfb8aa3b, v95
	v_mul_f32_e32 v99, 0xbfb8aa3b, v91
	v_exp_f32_e32 v98, v98
	v_exp_f32_e32 v99, v99
	v_add_f32_e32 v98, 1.0, v98
	v_add_f32_e32 v99, 1.0, v99
	v_rcp_f32_e32 v98, v98
	v_rcp_f32_e32 v99, v99
	v_mul_f32_e32 v95, v95, v98
	v_mul_f32_e32 v91, v91, v99
	v_mul_f32_e32 v98, 0xbfb8aa3b, v96
	v_mul_f32_e32 v99, 0xbfb8aa3b, v92
	v_exp_f32_e32 v98, v98
	v_exp_f32_e32 v99, v99
	v_add_f32_e32 v98, 1.0, v98
	v_add_f32_e32 v99, 1.0, v99
	v_rcp_f32_e32 v98, v98
	v_rcp_f32_e32 v99, v99
	v_mul_f32_e32 v96, v96, v98
	v_mul_f32_e32 v92, v92, v99
	v_mul_f32_e32 v98, 0xbfb8aa3b, v97
	v_mul_f32_e32 v99, 0xbfb8aa3b, v93
	v_exp_f32_e32 v98, v98
	v_exp_f32_e32 v99, v99
	v_add_f32_e32 v98, 1.0, v98
	v_add_f32_e32 v99, 1.0, v99
	v_rcp_f32_e32 v98, v98
	v_rcp_f32_e32 v99, v99
	v_mul_f32_e32 v97, v97, v98
	v_mul_f32_e32 v93, v93, v99
.LBB0_308:
	v_add_u32_e32 v100, 32, v150
	v_mov_b64_e32 v[98:99], s[18:19]
	v_mad_i64_i32 v[98:99], s[26:27], v100, s42, v[98:99]
	v_lshl_add_u64 v[98:99], v[142:143], 1, v[98:99]
	s_and_b64 vcc, exec, s[8:9]
	v_cvt_pk_bf16_f32 v94, v94, v95
	v_cvt_pk_bf16_f32 v95, v96, v97
	v_cvt_pk_bf16_f32 v96, v90, v91
	v_cvt_pk_bf16_f32 v97, v92, v93
	global_store_dwordx4 v[98:99], v[94:97], off
	s_cbranch_vccnz .LBB0_310
	s_and_b64 vcc, exec, s[6:7]
	s_cbranch_vccnz .Lsg_5
	v_mul_f32_e32 v90, 0xbfb8aa3b, v86
	v_mul_f32_e32 v91, 0xbfb8aa3b, v82
	v_exp_f32_e32 v90, v90
	v_exp_f32_e32 v91, v91
	v_add_f32_e32 v90, 1.0, v90
	v_add_f32_e32 v91, 1.0, v91
	v_rcp_f32_e32 v90, v90
	v_rcp_f32_e32 v91, v91
	v_mul_f32_e32 v86, v86, v90
	v_mul_f32_e32 v82, v82, v91
	v_mul_f32_e32 v90, 0xbfb8aa3b, v87
	v_mul_f32_e32 v91, 0xbfb8aa3b, v83
	v_exp_f32_e32 v90, v90
	v_exp_f32_e32 v91, v91
	v_add_f32_e32 v90, 1.0, v90
	v_add_f32_e32 v91, 1.0, v91
	v_rcp_f32_e32 v90, v90
	v_rcp_f32_e32 v91, v91
	v_mul_f32_e32 v87, v87, v90
	v_mul_f32_e32 v83, v83, v91
	v_mul_f32_e32 v90, 0xbfb8aa3b, v88
	v_mul_f32_e32 v91, 0xbfb8aa3b, v84
	v_exp_f32_e32 v90, v90
	v_exp_f32_e32 v91, v91
	v_add_f32_e32 v90, 1.0, v90
	v_add_f32_e32 v91, 1.0, v91
	v_rcp_f32_e32 v90, v90
	v_rcp_f32_e32 v91, v91
	v_mul_f32_e32 v88, v88, v90
	v_mul_f32_e32 v84, v84, v91
	v_mul_f32_e32 v90, 0xbfb8aa3b, v89
	v_mul_f32_e32 v91, 0xbfb8aa3b, v85
	v_exp_f32_e32 v90, v90
	v_exp_f32_e32 v91, v91
	v_add_f32_e32 v90, 1.0, v90
	v_add_f32_e32 v91, 1.0, v91
	v_rcp_f32_e32 v90, v90
	v_rcp_f32_e32 v91, v91
	v_mul_f32_e32 v89, v89, v90
	v_mul_f32_e32 v85, v85, v91
.LBB0_310:
	s_and_b64 vcc, exec, s[8:9]
	v_cvt_pk_bf16_f32 v86, v86, v87
	v_cvt_pk_bf16_f32 v87, v88, v89
	v_cvt_pk_bf16_f32 v88, v82, v83
	v_cvt_pk_bf16_f32 v89, v84, v85
	global_store_dwordx4 v[98:99], v[86:89], off offset:256
	s_cbranch_vccnz .LBB0_312
	s_and_b64 vcc, exec, s[6:7]
	s_cbranch_vccnz .Lsg_6
	v_mul_f32_e32 v82, 0xbfb8aa3b, v78
	v_mul_f32_e32 v83, 0xbfb8aa3b, v74
	v_exp_f32_e32 v82, v82
	v_exp_f32_e32 v83, v83
	v_add_f32_e32 v82, 1.0, v82
	v_add_f32_e32 v83, 1.0, v83
	v_rcp_f32_e32 v82, v82
	v_rcp_f32_e32 v83, v83
	v_mul_f32_e32 v78, v78, v82
	v_mul_f32_e32 v74, v74, v83
	v_mul_f32_e32 v82, 0xbfb8aa3b, v79
	v_mul_f32_e32 v83, 0xbfb8aa3b, v75
	v_exp_f32_e32 v82, v82
	v_exp_f32_e32 v83, v83
	v_add_f32_e32 v82, 1.0, v82
	v_add_f32_e32 v83, 1.0, v83
	v_rcp_f32_e32 v82, v82
	v_rcp_f32_e32 v83, v83
	v_mul_f32_e32 v79, v79, v82
	v_mul_f32_e32 v75, v75, v83
	v_mul_f32_e32 v82, 0xbfb8aa3b, v80
	v_mul_f32_e32 v83, 0xbfb8aa3b, v76
	v_exp_f32_e32 v82, v82
	v_exp_f32_e32 v83, v83
	v_add_f32_e32 v82, 1.0, v82
	v_add_f32_e32 v83, 1.0, v83
	v_rcp_f32_e32 v82, v82
	v_rcp_f32_e32 v83, v83
	v_mul_f32_e32 v80, v80, v82
	v_mul_f32_e32 v76, v76, v83
	v_mul_f32_e32 v82, 0xbfb8aa3b, v81
	v_mul_f32_e32 v83, 0xbfb8aa3b, v77
	v_exp_f32_e32 v82, v82
	v_exp_f32_e32 v83, v83
	v_add_f32_e32 v82, 1.0, v82
	v_add_f32_e32 v83, 1.0, v83
	v_rcp_f32_e32 v82, v82
	v_rcp_f32_e32 v83, v83
	v_mul_f32_e32 v81, v81, v82
	v_mul_f32_e32 v77, v77, v83
; __device__ __forceinline__ unsigned cvt_pk_bf16(float lo, float hi) { unsigned r; asm volatile("v_cvt_pk_bf16_f32 %0, %1, %2" : "=v"(r) : "v"(lo), "v"(hi)); return r; }
; __device__ __forceinline__ float sigmoidf_(float x) { return __builtin_amdgcn_rcpf(1.0f + __builtin_amdgcn_exp2f(-1.4426950408889634f * x)); }
;     __device__ __forceinline__ bool operator()(f32x4 (&acc)[2][2][4][2], const Unit& u, int wr, int wc, int fr, int fq) const {
;     ...
;             for (int m = 0; m < 4; ++m) { bf16_t* rowp = Z + (size_t)(row0 + ai * HALF + m * 16) * NZ + col0;
; #pragma unroll
;                 for (int bj = 0; bj < 2; ++bj) { f32x4 v0 = acc[ai][bj][m][0], v1 = acc[ai][bj][m][1];
;                     if (kind) {
; #pragma unroll
;                         for (int j = 0; j < 4; ++j) { const float s0 = sigmoidf_(v0[j]), s1 = sigmoidf_(v1[j]); v0[j] = kind == 1 ? v0[j] * s0 : s0; v1[j] = kind == 1 ? v1[j] * s1 : s1; } }
;                     u32x4 w; w.x = cvt_pk_bf16(v0[0], v0[1]); w.y = cvt_pk_bf16(v0[2], v0[3]); w.z = cvt_pk_bf16(v1[0], v1[1]); w.w = cvt_pk_bf16(v1[2], v1[3]);
;                     *(u32x4*)(rowp + bj * HALF) = w; } }
.LBB0_312:
	v_add_u32_e32 v84, 48, v150
	v_mov_b64_e32 v[82:83], s[18:19]
	v_mad_i64_i32 v[82:83], s[26:27], v84, s42, v[82:83]
	v_lshl_add_u64 v[82:83], v[142:143], 1, v[82:83]
	s_and_b64 vcc, exec, s[8:9]
	v_cvt_pk_bf16_f32 v78, v78, v79
	v_cvt_pk_bf16_f32 v79, v80, v81
	v_cvt_pk_bf16_f32 v80, v74, v75
	v_cvt_pk_bf16_f32 v81, v76, v77
	global_store_dwordx4 v[82:83], v[78:81], off
	s_cbranch_vccnz .LBB0_314
	s_and_b64 vcc, exec, s[6:7]
	s_cbranch_vccnz .Lsg_7
	v_mul_f32_e32 v74, 0xbfb8aa3b, v70
	v_mul_f32_e32 v75, 0xbfb8aa3b, v66
	v_exp_f32_e32 v74, v74
	v_exp_f32_e32 v75, v75
	v_add_f32_e32 v74, 1.0, v74
	v_add_f32_e32 v75, 1.0, v75
	v_rcp_f32_e32 v74, v74
	v_rcp_f32_e32 v75, v75
	v_mul_f32_e32 v70, v70, v74
	v_mul_f32_e32 v66, v66, v75
	v_mul_f32_e32 v74, 0xbfb8aa3b, v71
	v_mul_f32_e32 v75, 0xbfb8aa3b, v67
	v_exp_f32_e32 v74, v74
	v_exp_f32_e32 v75, v75
	v_add_f32_e32 v74, 1.0, v74
	v_add_f32_e32 v75, 1.0, v75
	v_rcp_f32_e32 v74, v74
	v_rcp_f32_e32 v75, v75
	v_mul_f32_e32 v71, v71, v74
	v_mul_f32_e32 v67, v67, v75
	v_mul_f32_e32 v74, 0xbfb8aa3b, v72
	v_mul_f32_e32 v75, 0xbfb8aa3b, v68
	v_exp_f32_e32 v74, v74
	v_exp_f32_e32 v75, v75
	v_add_f32_e32 v74, 1.0, v74
	v_add_f32_e32 v75, 1.0, v75
	v_rcp_f32_e32 v74, v74
	v_rcp_f32_e32 v75, v75
	v_mul_f32_e32 v72, v72, v74
	v_mul_f32_e32 v68, v68, v75
	v_mul_f32_e32 v74, 0xbfb8aa3b, v73
	v_mul_f32_e32 v75, 0xbfb8aa3b, v69
	v_exp_f32_e32 v74, v74
	v_exp_f32_e32 v75, v75
	v_add_f32_e32 v74, 1.0, v74
	v_add_f32_e32 v75, 1.0, v75
	v_rcp_f32_e32 v74, v74
	v_rcp_f32_e32 v75, v75
	v_mul_f32_e32 v73, v73, v74
	v_mul_f32_e32 v69, v69, v75
.LBB0_314:
	s_and_b64 vcc, exec, s[8:9]
	v_cvt_pk_bf16_f32 v70, v70, v71
	v_cvt_pk_bf16_f32 v71, v72, v73
	v_cvt_pk_bf16_f32 v72, v66, v67
	v_cvt_pk_bf16_f32 v73, v68, v69
	global_store_dwordx4 v[82:83], v[70:73], off offset:256
	s_cbranch_vccnz .LBB0_316
	s_and_b64 vcc, exec, s[6:7]
	s_cbranch_vccnz .Lsg_8
	v_mul_f32_e32 v66, 0xbfb8aa3b, v62
	v_mul_f32_e32 v67, 0xbfb8aa3b, v58
	v_exp_f32_e32 v66, v66
	v_exp_f32_e32 v67, v67
	v_add_f32_e32 v66, 1.0, v66
	v_add_f32_e32 v67, 1.0, v67
	v_rcp_f32_e32 v66, v66
	v_rcp_f32_e32 v67, v67
	v_mul_f32_e32 v62, v62, v66
	v_mul_f32_e32 v58, v58, v67
	v_mul_f32_e32 v66, 0xbfb8aa3b, v63
	v_mul_f32_e32 v67, 0xbfb8aa3b, v59
	v_exp_f32_e32 v66, v66
	v_exp_f32_e32 v67, v67
	v_add_f32_e32 v66, 1.0, v66
	v_add_f32_e32 v67, 1.0, v67
	v_rcp_f32_e32 v66, v66
	v_rcp_f32_e32 v67, v67
	v_mul_f32_e32 v63, v63, v66
	v_mul_f32_e32 v59, v59, v67
	v_mul_f32_e32 v66, 0xbfb8aa3b, v64
	v_mul_f32_e32 v67, 0xbfb8aa3b, v60
	v_exp_f32_e32 v66, v66
	v_exp_f32_e32 v67, v67
	v_add_f32_e32 v66, 1.0, v66
	v_add_f32_e32 v67, 1.0, v67
	v_rcp_f32_e32 v66, v66
	v_rcp_f32_e32 v67, v67
	v_mul_f32_e32 v64, v64, v66
	v_mul_f32_e32 v60, v60, v67
	v_mul_f32_e32 v66, 0xbfb8aa3b, v65
	v_mul_f32_e32 v67, 0xbfb8aa3b, v61
	v_exp_f32_e32 v66, v66
	v_exp_f32_e32 v67, v67
	v_add_f32_e32 v66, 1.0, v66
	v_add_f32_e32 v67, 1.0, v67
	v_rcp_f32_e32 v66, v66
	v_rcp_f32_e32 v67, v67
	v_mul_f32_e32 v65, v65, v66
	v_mul_f32_e32 v61, v61, v67
.LBB0_316:
	v_add_u32_e32 v68, 0x80, v150
	v_mov_b64_e32 v[66:67], s[18:19]
	v_mad_i64_i32 v[66:67], s[26:27], v68, s42, v[66:67]
	v_lshl_add_u64 v[66:67], v[142:143], 1, v[66:67]
	s_and_b64 vcc, exec, s[8:9]
	v_cvt_pk_bf16_f32 v62, v62, v63
	v_cvt_pk_bf16_f32 v63, v64, v65
	v_cvt_pk_bf16_f32 v64, v58, v59
	v_cvt_pk_bf16_f32 v65, v60, v61
	global_store_dwordx4 v[66:67], v[62:65], off
	s_cbranch_vccnz .LBB0_318
	s_and_b64 vcc, exec, s[6:7]
	s_cbranch_vccnz .Lsg_9
	v_mul_f32_e32 v58, 0xbfb8aa3b, v54
	v_mul_f32_e32 v59, 0xbfb8aa3b, v50
	v_exp_f32_e32 v58, v58
	v_exp_f32_e32 v59, v59
	v_add_f32_e32 v58, 1.0, v58
	v_add_f32_e32 v59, 1.0, v59
	v_rcp_f32_e32 v58, v58
	v_rcp_f32_e32 v59, v59
	v_mul_f32_e32 v54, v54, v58
	v_mul_f32_e32 v50, v50, v59
	v_mul_f32_e32 v58, 0xbfb8aa3b, v55
	v_mul_f32_e32 v59, 0xbfb8aa3b, v51
	v_exp_f32_e32 v58, v58
	v_exp_f32_e32 v59, v59
	v_add_f32_e32 v58, 1.0, v58
	v_add_f32_e32 v59, 1.0, v59
	v_rcp_f32_e32 v58, v58
	v_rcp_f32_e32 v59, v59
	v_mul_f32_e32 v55, v55, v58
	v_mul_f32_e32 v51, v51, v59
	v_mul_f32_e32 v58, 0xbfb8aa3b, v56
	v_mul_f32_e32 v59, 0xbfb8aa3b, v52
	v_exp_f32_e32 v58, v58
	v_exp_f32_e32 v59, v59
	v_add_f32_e32 v58, 1.0, v58
	v_add_f32_e32 v59, 1.0, v59
	v_rcp_f32_e32 v58, v58
	v_rcp_f32_e32 v59, v59
	v_mul_f32_e32 v56, v56, v58
	v_mul_f32_e32 v52, v52, v59
	v_mul_f32_e32 v58, 0xbfb8aa3b, v57
	v_mul_f32_e32 v59, 0xbfb8aa3b, v53
	v_exp_f32_e32 v58, v58
	v_exp_f32_e32 v59, v59
	v_add_f32_e32 v58, 1.0, v58
	v_add_f32_e32 v59, 1.0, v59
	v_rcp_f32_e32 v58, v58
	v_rcp_f32_e32 v59, v59
	v_mul_f32_e32 v57, v57, v58
	v_mul_f32_e32 v53, v53, v59
.LBB0_318:
	s_and_b64 vcc, exec, s[8:9]
	v_cvt_pk_bf16_f32 v54, v54, v55
	v_cvt_pk_bf16_f32 v55, v56, v57
	v_cvt_pk_bf16_f32 v56, v50, v51
	v_cvt_pk_bf16_f32 v57, v52, v53
	global_store_dwordx4 v[66:67], v[54:57], off offset:256
	s_cbranch_vccnz .LBB0_320
	s_and_b64 vcc, exec, s[6:7]
	s_cbranch_vccnz .Lsg_10
	v_mul_f32_e32 v50, 0xbfb8aa3b, v46
	v_mul_f32_e32 v51, 0xbfb8aa3b, v42
	v_exp_f32_e32 v50, v50
	v_exp_f32_e32 v51, v51
	v_add_f32_e32 v50, 1.0, v50
	v_add_f32_e32 v51, 1.0, v51
	v_rcp_f32_e32 v50, v50
	v_rcp_f32_e32 v51, v51
	v_mul_f32_e32 v46, v46, v50
	v_mul_f32_e32 v42, v42, v51
	v_mul_f32_e32 v50, 0xbfb8aa3b, v47
	v_mul_f32_e32 v51, 0xbfb8aa3b, v43
	v_exp_f32_e32 v50, v50
	v_exp_f32_e32 v51, v51
	v_add_f32_e32 v50, 1.0, v50
	v_add_f32_e32 v51, 1.0, v51
	v_rcp_f32_e32 v50, v50
	v_rcp_f32_e32 v51, v51
	v_mul_f32_e32 v47, v47, v50
	v_mul_f32_e32 v43, v43, v51
	v_mul_f32_e32 v50, 0xbfb8aa3b, v48
	v_mul_f32_e32 v51, 0xbfb8aa3b, v44
	v_exp_f32_e32 v50, v50
	v_exp_f32_e32 v51, v51
	v_add_f32_e32 v50, 1.0, v50
	v_add_f32_e32 v51, 1.0, v51
	v_rcp_f32_e32 v50, v50
	v_rcp_f32_e32 v51, v51
	v_mul_f32_e32 v48, v48, v50
	v_mul_f32_e32 v44, v44, v51
	v_mul_f32_e32 v50, 0xbfb8aa3b, v49
	v_mul_f32_e32 v51, 0xbfb8aa3b, v45
	v_exp_f32_e32 v50, v50
	v_exp_f32_e32 v51, v51
	v_add_f32_e32 v50, 1.0, v50
	v_add_f32_e32 v51, 1.0, v51
	v_rcp_f32_e32 v50, v50
	v_rcp_f32_e32 v51, v51
	v_mul_f32_e32 v49, v49, v50
	v_mul_f32_e32 v45, v45, v51
; __device__ __forceinline__ unsigned cvt_pk_bf16(float lo, float hi) { unsigned r; asm volatile("v_cvt_pk_bf16_f32 %0, %1, %2" : "=v"(r) : "v"(lo), "v"(hi)); return r; }
; __device__ __forceinline__ float sigmoidf_(float x) { return __builtin_amdgcn_rcpf(1.0f + __builtin_amdgcn_exp2f(-1.4426950408889634f * x)); }
;     __device__ __forceinline__ bool operator()(f32x4 (&acc)[2][2][4][2], const Unit& u, int wr, int wc, int fr, int fq) const {
;     ...
;             for (int m = 0; m < 4; ++m) { bf16_t* rowp = Z + (size_t)(row0 + ai * HALF + m * 16) * NZ + col0;
; #pragma unroll
;                 for (int bj = 0; bj < 2; ++bj) { f32x4 v0 = acc[ai][bj][m][0], v1 = acc[ai][bj][m][1];
;                     if (kind) {
; #pragma unroll
;                         for (int j = 0; j < 4; ++j) { const float s0 = sigmoidf_(v0[j]), s1 = sigmoidf_(v1[j]); v0[j] = kind == 1 ? v0[j] * s0 : s0; v1[j] = kind == 1 ? v1[j] * s1 : s1; } }
;                     u32x4 w; w.x = cvt_pk_bf16(v0[0], v0[1]); w.y = cvt_pk_bf16(v0[2], v0[3]); w.z = cvt_pk_bf16(v1[0], v1[1]); w.w = cvt_pk_bf16(v1[2], v1[3]);
;                     *(u32x4*)(rowp + bj * HALF) = w; } }
.LBB0_320:
	v_add_u32_e32 v52, 0x90, v150
	v_mov_b64_e32 v[50:51], s[18:19]
	v_mad_i64_i32 v[50:51], s[26:27], v52, s42, v[50:51]
	v_lshl_add_u64 v[50:51], v[142:143], 1, v[50:51]
	s_and_b64 vcc, exec, s[8:9]
	v_cvt_pk_bf16_f32 v46, v46, v47
	v_cvt_pk_bf16_f32 v47, v48, v49
	v_cvt_pk_bf16_f32 v48, v42, v43
	v_cvt_pk_bf16_f32 v49, v44, v45
	global_store_dwordx4 v[50:51], v[46:49], off
	s_cbranch_vccnz .LBB0_322
	s_and_b64 vcc, exec, s[6:7]
	s_cbranch_vccnz .Lsg_11
	v_mul_f32_e32 v42, 0xbfb8aa3b, v38
	v_mul_f32_e32 v43, 0xbfb8aa3b, v34
	v_exp_f32_e32 v42, v42
	v_exp_f32_e32 v43, v43
	v_add_f32_e32 v42, 1.0, v42
	v_add_f32_e32 v43, 1.0, v43
	v_rcp_f32_e32 v42, v42
	v_rcp_f32_e32 v43, v43
	v_mul_f32_e32 v38, v38, v42
	v_mul_f32_e32 v34, v34, v43
	v_mul_f32_e32 v42, 0xbfb8aa3b, v39
	v_mul_f32_e32 v43, 0xbfb8aa3b, v35
	v_exp_f32_e32 v42, v42
	v_exp_f32_e32 v43, v43
	v_add_f32_e32 v42, 1.0, v42
	v_add_f32_e32 v43, 1.0, v43
	v_rcp_f32_e32 v42, v42
	v_rcp_f32_e32 v43, v43
	v_mul_f32_e32 v39, v39, v42
	v_mul_f32_e32 v35, v35, v43
	v_mul_f32_e32 v42, 0xbfb8aa3b, v40
	v_mul_f32_e32 v43, 0xbfb8aa3b, v36
	v_exp_f32_e32 v42, v42
	v_exp_f32_e32 v43, v43
	v_add_f32_e32 v42, 1.0, v42
	v_add_f32_e32 v43, 1.0, v43
	v_rcp_f32_e32 v42, v42
	v_rcp_f32_e32 v43, v43
	v_mul_f32_e32 v40, v40, v42
	v_mul_f32_e32 v36, v36, v43
	v_mul_f32_e32 v42, 0xbfb8aa3b, v41
	v_mul_f32_e32 v43, 0xbfb8aa3b, v37
	v_exp_f32_e32 v42, v42
	v_exp_f32_e32 v43, v43
	v_add_f32_e32 v42, 1.0, v42
	v_add_f32_e32 v43, 1.0, v43
	v_rcp_f32_e32 v42, v42
	v_rcp_f32_e32 v43, v43
	v_mul_f32_e32 v41, v41, v42
	v_mul_f32_e32 v37, v37, v43
.LBB0_322:
	s_and_b64 vcc, exec, s[8:9]
	v_cvt_pk_bf16_f32 v38, v38, v39
	v_cvt_pk_bf16_f32 v39, v40, v41
	v_cvt_pk_bf16_f32 v40, v34, v35
	v_cvt_pk_bf16_f32 v41, v36, v37
	global_store_dwordx4 v[50:51], v[38:41], off offset:256
	s_cbranch_vccnz .LBB0_324
	s_and_b64 vcc, exec, s[6:7]
	s_cbranch_vccnz .Lsg_12
	v_mul_f32_e32 v34, 0xbfb8aa3b, v30
	v_mul_f32_e32 v35, 0xbfb8aa3b, v26
	v_exp_f32_e32 v34, v34
	v_exp_f32_e32 v35, v35
	v_add_f32_e32 v34, 1.0, v34
	v_add_f32_e32 v35, 1.0, v35
	v_rcp_f32_e32 v34, v34
	v_rcp_f32_e32 v35, v35
	v_mul_f32_e32 v30, v30, v34
	v_mul_f32_e32 v26, v26, v35
	v_mul_f32_e32 v34, 0xbfb8aa3b, v31
	v_mul_f32_e32 v35, 0xbfb8aa3b, v27
	v_exp_f32_e32 v34, v34
	v_exp_f32_e32 v35, v35
	v_add_f32_e32 v34, 1.0, v34
	v_add_f32_e32 v35, 1.0, v35
	v_rcp_f32_e32 v34, v34
	v_rcp_f32_e32 v35, v35
	v_mul_f32_e32 v31, v31, v34
	v_mul_f32_e32 v27, v27, v35
	v_mul_f32_e32 v34, 0xbfb8aa3b, v32
	v_mul_f32_e32 v35, 0xbfb8aa3b, v28
	v_exp_f32_e32 v34, v34
	v_exp_f32_e32 v35, v35
	v_add_f32_e32 v34, 1.0, v34
	v_add_f32_e32 v35, 1.0, v35
	v_rcp_f32_e32 v34, v34
	v_rcp_f32_e32 v35, v35
	v_mul_f32_e32 v32, v32, v34
	v_mul_f32_e32 v28, v28, v35
	v_mul_f32_e32 v34, 0xbfb8aa3b, v33
	v_mul_f32_e32 v35, 0xbfb8aa3b, v29
	v_exp_f32_e32 v34, v34
	v_exp_f32_e32 v35, v35
	v_add_f32_e32 v34, 1.0, v34
	v_add_f32_e32 v35, 1.0, v35
	v_rcp_f32_e32 v34, v34
	v_rcp_f32_e32 v35, v35
	v_mul_f32_e32 v33, v33, v34
	v_mul_f32_e32 v29, v29, v35
; __device__ __forceinline__ unsigned cvt_pk_bf16(float lo, float hi) { unsigned r; asm volatile("v_cvt_pk_bf16_f32 %0, %1, %2" : "=v"(r) : "v"(lo), "v"(hi)); return r; }
; __device__ __forceinline__ float sigmoidf_(float x) { return __builtin_amdgcn_rcpf(1.0f + __builtin_amdgcn_exp2f(-1.4426950408889634f * x)); }
;     __device__ __forceinline__ bool operator()(f32x4 (&acc)[2][2][4][2], const Unit& u, int wr, int wc, int fr, int fq) const {
;     ...
;             for (int m = 0; m < 4; ++m) { bf16_t* rowp = Z + (size_t)(row0 + ai * HALF + m * 16) * NZ + col0;
; #pragma unroll
;                 for (int bj = 0; bj < 2; ++bj) { f32x4 v0 = acc[ai][bj][m][0], v1 = acc[ai][bj][m][1];
;                     if (kind) {
; #pragma unroll
;                         for (int j = 0; j < 4; ++j) { const float s0 = sigmoidf_(v0[j]), s1 = sigmoidf_(v1[j]); v0[j] = kind == 1 ? v0[j] * s0 : s0; v1[j] = kind == 1 ? v1[j] * s1 : s1; } }
;                     u32x4 w; w.x = cvt_pk_bf16(v0[0], v0[1]); w.y = cvt_pk_bf16(v0[2], v0[3]); w.z = cvt_pk_bf16(v1[0], v1[1]); w.w = cvt_pk_bf16(v1[2], v1[3]);
;                     *(u32x4*)(rowp + bj * HALF) = w; } }
.LBB0_324:
	v_add_u32_e32 v36, 0xa0, v150
	v_mov_b64_e32 v[34:35], s[18:19]
	v_mad_i64_i32 v[34:35], s[26:27], v36, s42, v[34:35]
	v_lshl_add_u64 v[34:35], v[142:143], 1, v[34:35]
	s_and_b64 vcc, exec, s[8:9]
	v_cvt_pk_bf16_f32 v30, v30, v31
	v_cvt_pk_bf16_f32 v31, v32, v33
	v_cvt_pk_bf16_f32 v32, v26, v27
	v_cvt_pk_bf16_f32 v33, v28, v29
	global_store_dwordx4 v[34:35], v[30:33], off
	s_cbranch_vccnz .LBB0_326
	s_and_b64 vcc, exec, s[6:7]
	s_cbranch_vccnz .Lsg_13
	v_mul_f32_e32 v26, 0xbfb8aa3b, v22
	v_mul_f32_e32 v27, 0xbfb8aa3b, v18
	v_exp_f32_e32 v26, v26
	v_exp_f32_e32 v27, v27
	v_add_f32_e32 v26, 1.0, v26
	v_add_f32_e32 v27, 1.0, v27
	v_rcp_f32_e32 v26, v26
	v_rcp_f32_e32 v27, v27
	v_mul_f32_e32 v22, v22, v26
	v_mul_f32_e32 v18, v18, v27
	v_mul_f32_e32 v26, 0xbfb8aa3b, v23
	v_mul_f32_e32 v27, 0xbfb8aa3b, v19
	v_exp_f32_e32 v26, v26
	v_exp_f32_e32 v27, v27
	v_add_f32_e32 v26, 1.0, v26
	v_add_f32_e32 v27, 1.0, v27
	v_rcp_f32_e32 v26, v26
	v_rcp_f32_e32 v27, v27
	v_mul_f32_e32 v23, v23, v26
	v_mul_f32_e32 v19, v19, v27
	v_mul_f32_e32 v26, 0xbfb8aa3b, v24
	v_mul_f32_e32 v27, 0xbfb8aa3b, v20
	v_exp_f32_e32 v26, v26
	v_exp_f32_e32 v27, v27
	v_add_f32_e32 v26, 1.0, v26
	v_add_f32_e32 v27, 1.0, v27
	v_rcp_f32_e32 v26, v26
	v_rcp_f32_e32 v27, v27
	v_mul_f32_e32 v24, v24, v26
	v_mul_f32_e32 v20, v20, v27
	v_mul_f32_e32 v26, 0xbfb8aa3b, v25
	v_mul_f32_e32 v27, 0xbfb8aa3b, v21
	v_exp_f32_e32 v26, v26
	v_exp_f32_e32 v27, v27
	v_add_f32_e32 v26, 1.0, v26
	v_add_f32_e32 v27, 1.0, v27
	v_rcp_f32_e32 v26, v26
	v_rcp_f32_e32 v27, v27
	v_mul_f32_e32 v25, v25, v26
	v_mul_f32_e32 v21, v21, v27
.LBB0_326:
	s_and_b64 vcc, exec, s[8:9]
	v_cvt_pk_bf16_f32 v22, v22, v23
	v_cvt_pk_bf16_f32 v23, v24, v25
	v_cvt_pk_bf16_f32 v24, v18, v19
	v_cvt_pk_bf16_f32 v25, v20, v21
	global_store_dwordx4 v[34:35], v[22:25], off offset:256
	s_cbranch_vccnz .LBB0_328
	s_and_b64 vcc, exec, s[6:7]
	s_cbranch_vccnz .Lsg_14
	v_mul_f32_e32 v18, 0xbfb8aa3b, v14
	v_mul_f32_e32 v19, 0xbfb8aa3b, v10
	v_exp_f32_e32 v18, v18
	v_exp_f32_e32 v19, v19
	v_add_f32_e32 v18, 1.0, v18
	v_add_f32_e32 v19, 1.0, v19
	v_rcp_f32_e32 v18, v18
	v_rcp_f32_e32 v19, v19
	v_mul_f32_e32 v14, v14, v18
	v_mul_f32_e32 v10, v10, v19
	v_mul_f32_e32 v18, 0xbfb8aa3b, v15
	v_mul_f32_e32 v19, 0xbfb8aa3b, v11
	v_exp_f32_e32 v18, v18
	v_exp_f32_e32 v19, v19
	v_add_f32_e32 v18, 1.0, v18
	v_add_f32_e32 v19, 1.0, v19
	v_rcp_f32_e32 v18, v18
	v_rcp_f32_e32 v19, v19
	v_mul_f32_e32 v15, v15, v18
	v_mul_f32_e32 v11, v11, v19
	v_mul_f32_e32 v18, 0xbfb8aa3b, v16
	v_mul_f32_e32 v19, 0xbfb8aa3b, v12
	v_exp_f32_e32 v18, v18
	v_exp_f32_e32 v19, v19
	v_add_f32_e32 v18, 1.0, v18
	v_add_f32_e32 v19, 1.0, v19
	v_rcp_f32_e32 v18, v18
	v_rcp_f32_e32 v19, v19
	v_mul_f32_e32 v16, v16, v18
	v_mul_f32_e32 v12, v12, v19
	v_mul_f32_e32 v18, 0xbfb8aa3b, v17
	v_mul_f32_e32 v19, 0xbfb8aa3b, v13
	v_exp_f32_e32 v18, v18
	v_exp_f32_e32 v19, v19
	v_add_f32_e32 v18, 1.0, v18
	v_add_f32_e32 v19, 1.0, v19
	v_rcp_f32_e32 v18, v18
	v_rcp_f32_e32 v19, v19
	v_mul_f32_e32 v17, v17, v18
	v_mul_f32_e32 v13, v13, v19
.LBB0_328:
	v_add_u32_e32 v20, 0xb0, v150
	v_mov_b64_e32 v[18:19], s[18:19]
	v_mad_i64_i32 v[18:19], s[26:27], v20, s42, v[18:19]
	v_lshl_add_u64 v[18:19], v[142:143], 1, v[18:19]
	s_and_b64 vcc, exec, s[8:9]
	v_cvt_pk_bf16_f32 v14, v14, v15
	v_cvt_pk_bf16_f32 v15, v16, v17
	v_cvt_pk_bf16_f32 v16, v10, v11
	v_cvt_pk_bf16_f32 v17, v12, v13
	global_store_dwordx4 v[18:19], v[14:17], off
	s_cbranch_vccnz .LBB0_330
	s_and_b64 vcc, exec, s[6:7]
	s_cbranch_vccnz .Lsg_15
	v_mul_f32_e32 v10, 0xbfb8aa3b, v6
	v_mul_f32_e32 v11, 0xbfb8aa3b, v2
	v_exp_f32_e32 v10, v10
	v_exp_f32_e32 v11, v11
	v_add_f32_e32 v10, 1.0, v10
	v_add_f32_e32 v11, 1.0, v11
	v_rcp_f32_e32 v10, v10
	v_rcp_f32_e32 v11, v11
	v_mul_f32_e32 v6, v6, v10
	v_mul_f32_e32 v2, v2, v11
	v_mul_f32_e32 v10, 0xbfb8aa3b, v7
	v_mul_f32_e32 v11, 0xbfb8aa3b, v3
	v_exp_f32_e32 v10, v10
	v_exp_f32_e32 v11, v11
	v_add_f32_e32 v10, 1.0, v10
	v_add_f32_e32 v11, 1.0, v11
	v_rcp_f32_e32 v10, v10
	v_rcp_f32_e32 v11, v11
	v_mul_f32_e32 v7, v7, v10
	v_mul_f32_e32 v3, v3, v11
	v_mul_f32_e32 v10, 0xbfb8aa3b, v8
	v_mul_f32_e32 v11, 0xbfb8aa3b, v4
	v_exp_f32_e32 v10, v10
	v_exp_f32_e32 v11, v11
	v_add_f32_e32 v10, 1.0, v10
	v_add_f32_e32 v11, 1.0, v11
	v_rcp_f32_e32 v10, v10
	v_rcp_f32_e32 v11, v11
	v_mul_f32_e32 v8, v8, v10
	v_mul_f32_e32 v4, v4, v11
	v_mul_f32_e32 v10, 0xbfb8aa3b, v9
	v_mul_f32_e32 v11, 0xbfb8aa3b, v5
	v_exp_f32_e32 v10, v10
	v_exp_f32_e32 v11, v11
	v_add_f32_e32 v10, 1.0, v10
	v_add_f32_e32 v11, 1.0, v11
	v_rcp_f32_e32 v10, v10
	v_rcp_f32_e32 v11, v11
	v_mul_f32_e32 v9, v9, v10
	v_mul_f32_e32 v5, v5, v11

; __device__ __forceinline__ unsigned cvt_pk_bf16(float lo, float hi) { unsigned r; asm volatile("v_cvt_pk_bf16_f32 %0, %1, %2" : "=v"(r) : "v"(lo), "v"(hi)); return r; }
; __device__ __forceinline__ float sigmoidf_(float x) { return __builtin_amdgcn_rcpf(1.0f + __builtin_amdgcn_exp2f(-1.4426950408889634f * x)); }
;     __device__ __forceinline__ bool operator()(f32x4 (&acc)[2][2][4][2], const Unit& u, int wr, int wc, int fr, int fq) const {
;     ...
;                     if (kind) {
; #pragma unroll
;                         for (int j = 0; j < 4; ++j) { const float s0 = sigmoidf_(v0[j]), s1 = sigmoidf_(v1[j]); v0[j] = kind == 1 ? v0[j] * s0 : s0; v1[j] = kind == 1 ? v1[j] * s1 : s1; } }
;                     u32x4 w; w.x = cvt_pk_bf16(v0[0], v0[1]); w.y = cvt_pk_bf16(v0[2], v0[3]); w.z = cvt_pk_bf16(v1[0], v1[1]); w.w = cvt_pk_bf16(v1[2], v1[3]);
;                     *(u32x4*)(rowp + bj * HALF) = w; } }
.Lsg_0:
	v_mul_f32_e32 v142, 0xbfb8aa3b, v128
	v_mul_f32_e32 v143, 0xbfb8aa3b, v124
	v_exp_f32_e32 v142, v142
	v_exp_f32_e32 v143, v143
	v_add_f32_e32 v142, 1.0, v142
	v_add_f32_e32 v143, 1.0, v143
	v_rcp_f32_e32 v128, v142
	v_rcp_f32_e32 v124, v143
	v_mul_f32_e32 v142, 0xbfb8aa3b, v129
	v_mul_f32_e32 v143, 0xbfb8aa3b, v125
	v_exp_f32_e32 v142, v142
	v_exp_f32_e32 v143, v143
	v_add_f32_e32 v142, 1.0, v142
	v_add_f32_e32 v143, 1.0, v143
	v_rcp_f32_e32 v129, v142
	v_rcp_f32_e32 v125, v143
	v_mul_f32_e32 v142, 0xbfb8aa3b, v130
	v_mul_f32_e32 v143, 0xbfb8aa3b, v126
	v_exp_f32_e32 v142, v142
	v_exp_f32_e32 v143, v143
	v_add_f32_e32 v142, 1.0, v142
	v_add_f32_e32 v143, 1.0, v143
	v_rcp_f32_e32 v130, v142
	v_rcp_f32_e32 v126, v143
	v_mul_f32_e32 v142, 0xbfb8aa3b, v131
	v_mul_f32_e32 v143, 0xbfb8aa3b, v127
	v_exp_f32_e32 v142, v142
	v_exp_f32_e32 v143, v143
	v_add_f32_e32 v142, 1.0, v142
	v_add_f32_e32 v143, 1.0, v143
	v_rcp_f32_e32 v131, v142
	v_rcp_f32_e32 v127, v143
	s_branch .LBB0_300
.Lsg_1:
	v_mul_f32_e32 v124, 0xbfb8aa3b, v120
	v_mul_f32_e32 v125, 0xbfb8aa3b, v116
	v_exp_f32_e32 v124, v124
	v_exp_f32_e32 v125, v125
	v_add_f32_e32 v124, 1.0, v124
	v_add_f32_e32 v125, 1.0, v125
	v_rcp_f32_e32 v120, v124
	v_rcp_f32_e32 v116, v125
	v_mul_f32_e32 v124, 0xbfb8aa3b, v121
	v_mul_f32_e32 v125, 0xbfb8aa3b, v117
	v_exp_f32_e32 v124, v124
	v_exp_f32_e32 v125, v125
	v_add_f32_e32 v124, 1.0, v124
	v_add_f32_e32 v125, 1.0, v125
	v_rcp_f32_e32 v121, v124
	v_rcp_f32_e32 v117, v125
	v_mul_f32_e32 v124, 0xbfb8aa3b, v122
	v_mul_f32_e32 v125, 0xbfb8aa3b, v118
	v_exp_f32_e32 v124, v124
	v_exp_f32_e32 v125, v125
	v_add_f32_e32 v124, 1.0, v124
	v_add_f32_e32 v125, 1.0, v125
	v_rcp_f32_e32 v122, v124
	v_rcp_f32_e32 v118, v125
	v_mul_f32_e32 v124, 0xbfb8aa3b, v123
	v_mul_f32_e32 v125, 0xbfb8aa3b, v119
	v_exp_f32_e32 v124, v124
	v_exp_f32_e32 v125, v125
	v_add_f32_e32 v124, 1.0, v124
	v_add_f32_e32 v125, 1.0, v125
	v_rcp_f32_e32 v123, v124
	v_rcp_f32_e32 v119, v125
	s_branch .LBB0_302
.Lsg_2:
	v_mul_f32_e32 v116, 0xbfb8aa3b, v110
	v_mul_f32_e32 v117, 0xbfb8aa3b, v106
	v_exp_f32_e32 v116, v116
	v_exp_f32_e32 v117, v117
	v_add_f32_e32 v116, 1.0, v116
	v_add_f32_e32 v117, 1.0, v117
	v_rcp_f32_e32 v110, v116
	v_rcp_f32_e32 v106, v117
	v_mul_f32_e32 v116, 0xbfb8aa3b, v111
	v_mul_f32_e32 v117, 0xbfb8aa3b, v107
	v_exp_f32_e32 v116, v116
	v_exp_f32_e32 v117, v117
	v_add_f32_e32 v116, 1.0, v116
	v_add_f32_e32 v117, 1.0, v117
	v_rcp_f32_e32 v111, v116
	v_rcp_f32_e32 v107, v117
	v_mul_f32_e32 v116, 0xbfb8aa3b, v112
	v_mul_f32_e32 v117, 0xbfb8aa3b, v108
	v_exp_f32_e32 v116, v116
	v_exp_f32_e32 v117, v117
	v_add_f32_e32 v116, 1.0, v116
	v_add_f32_e32 v117, 1.0, v117
	v_rcp_f32_e32 v112, v116
	v_rcp_f32_e32 v108, v117
	v_mul_f32_e32 v116, 0xbfb8aa3b, v113
	v_mul_f32_e32 v117, 0xbfb8aa3b, v109
	v_exp_f32_e32 v116, v116
	v_exp_f32_e32 v117, v117
	v_add_f32_e32 v116, 1.0, v116
	v_add_f32_e32 v117, 1.0, v117
	v_rcp_f32_e32 v113, v116
	v_rcp_f32_e32 v109, v117
	s_branch .LBB0_304
.Lsg_3:
	v_mul_f32_e32 v106, 0xbfb8aa3b, v102
	v_mul_f32_e32 v107, 0xbfb8aa3b, v98
	v_exp_f32_e32 v106, v106
	v_exp_f32_e32 v107, v107
	v_add_f32_e32 v106, 1.0, v106
	v_add_f32_e32 v107, 1.0, v107
	v_rcp_f32_e32 v102, v106
	v_rcp_f32_e32 v98, v107
	v_mul_f32_e32 v106, 0xbfb8aa3b, v103
	v_mul_f32_e32 v107, 0xbfb8aa3b, v99
	v_exp_f32_e32 v106, v106
	v_exp_f32_e32 v107, v107
	v_add_f32_e32 v106, 1.0, v106
	v_add_f32_e32 v107, 1.0, v107
	v_rcp_f32_e32 v103, v106
	v_rcp_f32_e32 v99, v107
	v_mul_f32_e32 v106, 0xbfb8aa3b, v104
	v_mul_f32_e32 v107, 0xbfb8aa3b, v100
	v_exp_f32_e32 v106, v106
	v_exp_f32_e32 v107, v107
	v_add_f32_e32 v106, 1.0, v106
	v_add_f32_e32 v107, 1.0, v107
	v_rcp_f32_e32 v104, v106
	v_rcp_f32_e32 v100, v107
	v_mul_f32_e32 v106, 0xbfb8aa3b, v105
	v_mul_f32_e32 v107, 0xbfb8aa3b, v101
	v_exp_f32_e32 v106, v106
	v_exp_f32_e32 v107, v107
	v_add_f32_e32 v106, 1.0, v106
	v_add_f32_e32 v107, 1.0, v107
	v_rcp_f32_e32 v105, v106
	v_rcp_f32_e32 v101, v107
	s_branch .LBB0_306
.Lsg_4:
	v_mul_f32_e32 v98, 0xbfb8aa3b, v94
	v_mul_f32_e32 v99, 0xbfb8aa3b, v90
	v_exp_f32_e32 v98, v98
	v_exp_f32_e32 v99, v99
	v_add_f32_e32 v98, 1.0, v98
	v_add_f32_e32 v99, 1.0, v99
	v_rcp_f32_e32 v94, v98
	v_rcp_f32_e32 v90, v99
	v_mul_f32_e32 v98, 0xbfb8aa3b, v95
	v_mul_f32_e32 v99, 0xbfb8aa3b, v91
	v_exp_f32_e32 v98, v98
	v_exp_f32_e32 v99, v99
	v_add_f32_e32 v98, 1.0, v98
	v_add_f32_e32 v99, 1.0, v99
	v_rcp_f32_e32 v95, v98
	v_rcp_f32_e32 v91, v99
	v_mul_f32_e32 v98, 0xbfb8aa3b, v96
	v_mul_f32_e32 v99, 0xbfb8aa3b, v92
	v_exp_f32_e32 v98, v98
	v_exp_f32_e32 v99, v99
	v_add_f32_e32 v98, 1.0, v98
	v_add_f32_e32 v99, 1.0, v99
	v_rcp_f32_e32 v96, v98
	v_rcp_f32_e32 v92, v99
	v_mul_f32_e32 v98, 0xbfb8aa3b, v97
	v_mul_f32_e32 v99, 0xbfb8aa3b, v93
	v_exp_f32_e32 v98, v98
	v_exp_f32_e32 v99, v99
	v_add_f32_e32 v98, 1.0, v98
	v_add_f32_e32 v99, 1.0, v99
	v_rcp_f32_e32 v97, v98
	v_rcp_f32_e32 v93, v99
	s_branch .LBB0_308
.Lsg_5:
	v_mul_f32_e32 v90, 0xbfb8aa3b, v86
	v_mul_f32_e32 v91, 0xbfb8aa3b, v82
	v_exp_f32_e32 v90, v90
	v_exp_f32_e32 v91, v91
	v_add_f32_e32 v90, 1.0, v90
	v_add_f32_e32 v91, 1.0, v91
	v_rcp_f32_e32 v86, v90
	v_rcp_f32_e32 v82, v91
	v_mul_f32_e32 v90, 0xbfb8aa3b, v87
	v_mul_f32_e32 v91, 0xbfb8aa3b, v83
	v_exp_f32_e32 v90, v90
	v_exp_f32_e32 v91, v91
	v_add_f32_e32 v90, 1.0, v90
	v_add_f32_e32 v91, 1.0, v91
	v_rcp_f32_e32 v87, v90
	v_rcp_f32_e32 v83, v91
	v_mul_f32_e32 v90, 0xbfb8aa3b, v88
	v_mul_f32_e32 v91, 0xbfb8aa3b, v84
	v_exp_f32_e32 v90, v90
	v_exp_f32_e32 v91, v91
	v_add_f32_e32 v90, 1.0, v90
	v_add_f32_e32 v91, 1.0, v91
	v_rcp_f32_e32 v88, v90
	v_rcp_f32_e32 v84, v91
	v_mul_f32_e32 v90, 0xbfb8aa3b, v89
	v_mul_f32_e32 v91, 0xbfb8aa3b, v85
	v_exp_f32_e32 v90, v90
	v_exp_f32_e32 v91, v91
	v_add_f32_e32 v90, 1.0, v90
	v_add_f32_e32 v91, 1.0, v91
	v_rcp_f32_e32 v89, v90
	v_rcp_f32_e32 v85, v91
	s_branch .LBB0_310
; __device__ __forceinline__ unsigned cvt_pk_bf16(float lo, float hi) { unsigned r; asm volatile("v_cvt_pk_bf16_f32 %0, %1, %2" : "=v"(r) : "v"(lo), "v"(hi)); return r; }
; __device__ __forceinline__ float sigmoidf_(float x) { return __builtin_amdgcn_rcpf(1.0f + __builtin_amdgcn_exp2f(-1.4426950408889634f * x)); }
;     __device__ __forceinline__ bool operator()(f32x4 (&acc)[2][2][4][2], const Unit& u, int wr, int wc, int fr, int fq) const {
;     ...
;                     if (kind) {
; #pragma unroll
;                         for (int j = 0; j < 4; ++j) { const float s0 = sigmoidf_(v0[j]), s1 = sigmoidf_(v1[j]); v0[j] = kind == 1 ? v0[j] * s0 : s0; v1[j] = kind == 1 ? v1[j] * s1 : s1; } }
;                     u32x4 w; w.x = cvt_pk_bf16(v0[0], v0[1]); w.y = cvt_pk_bf16(v0[2], v0[3]); w.z = cvt_pk_bf16(v1[0], v1[1]); w.w = cvt_pk_bf16(v1[2], v1[3]);
;                     *(u32x4*)(rowp + bj * HALF) = w; } }
.Lsg_6:
	v_mul_f32_e32 v82, 0xbfb8aa3b, v78
	v_mul_f32_e32 v83, 0xbfb8aa3b, v74
	v_exp_f32_e32 v82, v82
	v_exp_f32_e32 v83, v83
	v_add_f32_e32 v82, 1.0, v82
	v_add_f32_e32 v83, 1.0, v83
	v_rcp_f32_e32 v78, v82
	v_rcp_f32_e32 v74, v83
	v_mul_f32_e32 v82, 0xbfb8aa3b, v79
	v_mul_f32_e32 v83, 0xbfb8aa3b, v75
	v_exp_f32_e32 v82, v82
	v_exp_f32_e32 v83, v83
	v_add_f32_e32 v82, 1.0, v82
	v_add_f32_e32 v83, 1.0, v83
	v_rcp_f32_e32 v79, v82
	v_rcp_f32_e32 v75, v83
	v_mul_f32_e32 v82, 0xbfb8aa3b, v80
	v_mul_f32_e32 v83, 0xbfb8aa3b, v76
	v_exp_f32_e32 v82, v82
	v_exp_f32_e32 v83, v83
	v_add_f32_e32 v82, 1.0, v82
	v_add_f32_e32 v83, 1.0, v83
	v_rcp_f32_e32 v80, v82
	v_rcp_f32_e32 v76, v83
	v_mul_f32_e32 v82, 0xbfb8aa3b, v81
	v_mul_f32_e32 v83, 0xbfb8aa3b, v77
	v_exp_f32_e32 v82, v82
	v_exp_f32_e32 v83, v83
	v_add_f32_e32 v82, 1.0, v82
	v_add_f32_e32 v83, 1.0, v83
	v_rcp_f32_e32 v81, v82
	v_rcp_f32_e32 v77, v83
	s_branch .LBB0_312
.Lsg_7:
	v_mul_f32_e32 v74, 0xbfb8aa3b, v70
	v_mul_f32_e32 v75, 0xbfb8aa3b, v66
	v_exp_f32_e32 v74, v74
	v_exp_f32_e32 v75, v75
	v_add_f32_e32 v74, 1.0, v74
	v_add_f32_e32 v75, 1.0, v75
	v_rcp_f32_e32 v70, v74
	v_rcp_f32_e32 v66, v75
	v_mul_f32_e32 v74, 0xbfb8aa3b, v71
	v_mul_f32_e32 v75, 0xbfb8aa3b, v67
	v_exp_f32_e32 v74, v74
	v_exp_f32_e32 v75, v75
	v_add_f32_e32 v74, 1.0, v74
	v_add_f32_e32 v75, 1.0, v75
	v_rcp_f32_e32 v71, v74
	v_rcp_f32_e32 v67, v75
	v_mul_f32_e32 v74, 0xbfb8aa3b, v72
	v_mul_f32_e32 v75, 0xbfb8aa3b, v68
	v_exp_f32_e32 v74, v74
	v_exp_f32_e32 v75, v75
	v_add_f32_e32 v74, 1.0, v74
	v_add_f32_e32 v75, 1.0, v75
	v_rcp_f32_e32 v72, v74
	v_rcp_f32_e32 v68, v75
	v_mul_f32_e32 v74, 0xbfb8aa3b, v73
	v_mul_f32_e32 v75, 0xbfb8aa3b, v69
	v_exp_f32_e32 v74, v74
	v_exp_f32_e32 v75, v75
	v_add_f32_e32 v74, 1.0, v74
	v_add_f32_e32 v75, 1.0, v75
	v_rcp_f32_e32 v73, v74
	v_rcp_f32_e32 v69, v75
	s_branch .LBB0_314
.Lsg_8:
	v_mul_f32_e32 v66, 0xbfb8aa3b, v62
	v_mul_f32_e32 v67, 0xbfb8aa3b, v58
	v_exp_f32_e32 v66, v66
	v_exp_f32_e32 v67, v67
	v_add_f32_e32 v66, 1.0, v66
	v_add_f32_e32 v67, 1.0, v67
	v_rcp_f32_e32 v62, v66
	v_rcp_f32_e32 v58, v67
	v_mul_f32_e32 v66, 0xbfb8aa3b, v63
	v_mul_f32_e32 v67, 0xbfb8aa3b, v59
	v_exp_f32_e32 v66, v66
	v_exp_f32_e32 v67, v67
	v_add_f32_e32 v66, 1.0, v66
	v_add_f32_e32 v67, 1.0, v67
	v_rcp_f32_e32 v63, v66
	v_rcp_f32_e32 v59, v67
	v_mul_f32_e32 v66, 0xbfb8aa3b, v64
	v_mul_f32_e32 v67, 0xbfb8aa3b, v60
	v_exp_f32_e32 v66, v66
	v_exp_f32_e32 v67, v67
	v_add_f32_e32 v66, 1.0, v66
	v_add_f32_e32 v67, 1.0, v67
	v_rcp_f32_e32 v64, v66
	v_rcp_f32_e32 v60, v67
	v_mul_f32_e32 v66, 0xbfb8aa3b, v65
	v_mul_f32_e32 v67, 0xbfb8aa3b, v61
	v_exp_f32_e32 v66, v66
	v_exp_f32_e32 v67, v67
	v_add_f32_e32 v66, 1.0, v66
	v_add_f32_e32 v67, 1.0, v67
	v_rcp_f32_e32 v65, v66
	v_rcp_f32_e32 v61, v67
	s_branch .LBB0_316
.Lsg_9:
	v_mul_f32_e32 v58, 0xbfb8aa3b, v54
	v_mul_f32_e32 v59, 0xbfb8aa3b, v50
	v_exp_f32_e32 v58, v58
	v_exp_f32_e32 v59, v59
	v_add_f32_e32 v58, 1.0, v58
	v_add_f32_e32 v59, 1.0, v59
	v_rcp_f32_e32 v54, v58
	v_rcp_f32_e32 v50, v59
	v_mul_f32_e32 v58, 0xbfb8aa3b, v55
	v_mul_f32_e32 v59, 0xbfb8aa3b, v51
	v_exp_f32_e32 v58, v58
	v_exp_f32_e32 v59, v59
	v_add_f32_e32 v58, 1.0, v58
	v_add_f32_e32 v59, 1.0, v59
	v_rcp_f32_e32 v55, v58
	v_rcp_f32_e32 v51, v59
	v_mul_f32_e32 v58, 0xbfb8aa3b, v56
	v_mul_f32_e32 v59, 0xbfb8aa3b, v52
	v_exp_f32_e32 v58, v58
	v_exp_f32_e32 v59, v59
	v_add_f32_e32 v58, 1.0, v58
	v_add_f32_e32 v59, 1.0, v59
	v_rcp_f32_e32 v56, v58
	v_rcp_f32_e32 v52, v59
	v_mul_f32_e32 v58, 0xbfb8aa3b, v57
	v_mul_f32_e32 v59, 0xbfb8aa3b, v53
	v_exp_f32_e32 v58, v58
	v_exp_f32_e32 v59, v59
	v_add_f32_e32 v58, 1.0, v58
	v_add_f32_e32 v59, 1.0, v59
	v_rcp_f32_e32 v57, v58
	v_rcp_f32_e32 v53, v59
	s_branch .LBB0_318
.Lsg_10:
	v_mul_f32_e32 v50, 0xbfb8aa3b, v46
	v_mul_f32_e32 v51, 0xbfb8aa3b, v42
	v_exp_f32_e32 v50, v50
	v_exp_f32_e32 v51, v51
	v_add_f32_e32 v50, 1.0, v50
	v_add_f32_e32 v51, 1.0, v51
	v_rcp_f32_e32 v46, v50
	v_rcp_f32_e32 v42, v51
	v_mul_f32_e32 v50, 0xbfb8aa3b, v47
	v_mul_f32_e32 v51, 0xbfb8aa3b, v43
	v_exp_f32_e32 v50, v50
	v_exp_f32_e32 v51, v51
	v_add_f32_e32 v50, 1.0, v50
	v_add_f32_e32 v51, 1.0, v51
	v_rcp_f32_e32 v47, v50
	v_rcp_f32_e32 v43, v51
	v_mul_f32_e32 v50, 0xbfb8aa3b, v48
	v_mul_f32_e32 v51, 0xbfb8aa3b, v44
	v_exp_f32_e32 v50, v50
	v_exp_f32_e32 v51, v51
	v_add_f32_e32 v50, 1.0, v50
	v_add_f32_e32 v51, 1.0, v51
	v_rcp_f32_e32 v48, v50
	v_rcp_f32_e32 v44, v51
	v_mul_f32_e32 v50, 0xbfb8aa3b, v49
	v_mul_f32_e32 v51, 0xbfb8aa3b, v45
	v_exp_f32_e32 v50, v50
	v_exp_f32_e32 v51, v51
	v_add_f32_e32 v50, 1.0, v50
	v_add_f32_e32 v51, 1.0, v51
	v_rcp_f32_e32 v49, v50
	v_rcp_f32_e32 v45, v51
	s_branch .LBB0_320
; __device__ __forceinline__ unsigned cvt_pk_bf16(float lo, float hi) { unsigned r; asm volatile("v_cvt_pk_bf16_f32 %0, %1, %2" : "=v"(r) : "v"(lo), "v"(hi)); return r; }
; __device__ __forceinline__ float sigmoidf_(float x) { return __builtin_amdgcn_rcpf(1.0f + __builtin_amdgcn_exp2f(-1.4426950408889634f * x)); }
;     __device__ __forceinline__ bool operator()(f32x4 (&acc)[2][2][4][2], const Unit& u, int wr, int wc, int fr, int fq) const {
;     ...
;                     if (kind) {
; #pragma unroll
;                         for (int j = 0; j < 4; ++j) { const float s0 = sigmoidf_(v0[j]), s1 = sigmoidf_(v1[j]); v0[j] = kind == 1 ? v0[j] * s0 : s0; v1[j] = kind == 1 ? v1[j] * s1 : s1; } }
;                     u32x4 w; w.x = cvt_pk_bf16(v0[0], v0[1]); w.y = cvt_pk_bf16(v0[2], v0[3]); w.z = cvt_pk_bf16(v1[0], v1[1]); w.w = cvt_pk_bf16(v1[2], v1[3]);
;                     *(u32x4*)(rowp + bj * HALF) = w; } }
.Lsg_11:
	v_mul_f32_e32 v42, 0xbfb8aa3b, v38
	v_mul_f32_e32 v43, 0xbfb8aa3b, v34
	v_exp_f32_e32 v42, v42
	v_exp_f32_e32 v43, v43
	v_add_f32_e32 v42, 1.0, v42
	v_add_f32_e32 v43, 1.0, v43
	v_rcp_f32_e32 v38, v42
	v_rcp_f32_e32 v34, v43
	v_mul_f32_e32 v42, 0xbfb8aa3b, v39
	v_mul_f32_e32 v43, 0xbfb8aa3b, v35
	v_exp_f32_e32 v42, v42
	v_exp_f32_e32 v43, v43
	v_add_f32_e32 v42, 1.0, v42
	v_add_f32_e32 v43, 1.0, v43
	v_rcp_f32_e32 v39, v42
	v_rcp_f32_e32 v35, v43
	v_mul_f32_e32 v42, 0xbfb8aa3b, v40
	v_mul_f32_e32 v43, 0xbfb8aa3b, v36
	v_exp_f32_e32 v42, v42
	v_exp_f32_e32 v43, v43
	v_add_f32_e32 v42, 1.0, v42
	v_add_f32_e32 v43, 1.0, v43
	v_rcp_f32_e32 v40, v42
	v_rcp_f32_e32 v36, v43
	v_mul_f32_e32 v42, 0xbfb8aa3b, v41
	v_mul_f32_e32 v43, 0xbfb8aa3b, v37
	v_exp_f32_e32 v42, v42
	v_exp_f32_e32 v43, v43
	v_add_f32_e32 v42, 1.0, v42
	v_add_f32_e32 v43, 1.0, v43
	v_rcp_f32_e32 v41, v42
	v_rcp_f32_e32 v37, v43
	s_branch .LBB0_322
.Lsg_12:
	v_mul_f32_e32 v34, 0xbfb8aa3b, v30
	v_mul_f32_e32 v35, 0xbfb8aa3b, v26
	v_exp_f32_e32 v34, v34
	v_exp_f32_e32 v35, v35
	v_add_f32_e32 v34, 1.0, v34
	v_add_f32_e32 v35, 1.0, v35
	v_rcp_f32_e32 v30, v34
	v_rcp_f32_e32 v26, v35
	v_mul_f32_e32 v34, 0xbfb8aa3b, v31
	v_mul_f32_e32 v35, 0xbfb8aa3b, v27
	v_exp_f32_e32 v34, v34
	v_exp_f32_e32 v35, v35
	v_add_f32_e32 v34, 1.0, v34
	v_add_f32_e32 v35, 1.0, v35
	v_rcp_f32_e32 v31, v34
	v_rcp_f32_e32 v27, v35
	v_mul_f32_e32 v34, 0xbfb8aa3b, v32
	v_mul_f32_e32 v35, 0xbfb8aa3b, v28
	v_exp_f32_e32 v34, v34
	v_exp_f32_e32 v35, v35
	v_add_f32_e32 v34, 1.0, v34
	v_add_f32_e32 v35, 1.0, v35
	v_rcp_f32_e32 v32, v34
	v_rcp_f32_e32 v28, v35
	v_mul_f32_e32 v34, 0xbfb8aa3b, v33
	v_mul_f32_e32 v35, 0xbfb8aa3b, v29
	v_exp_f32_e32 v34, v34
	v_exp_f32_e32 v35, v35
	v_add_f32_e32 v34, 1.0, v34
	v_add_f32_e32 v35, 1.0, v35
	v_rcp_f32_e32 v33, v34
	v_rcp_f32_e32 v29, v35
	s_branch .LBB0_324
.Lsg_13:
	v_mul_f32_e32 v26, 0xbfb8aa3b, v22
	v_mul_f32_e32 v27, 0xbfb8aa3b, v18
	v_exp_f32_e32 v26, v26
	v_exp_f32_e32 v27, v27
	v_add_f32_e32 v26, 1.0, v26
	v_add_f32_e32 v27, 1.0, v27
	v_rcp_f32_e32 v22, v26
	v_rcp_f32_e32 v18, v27
	v_mul_f32_e32 v26, 0xbfb8aa3b, v23
	v_mul_f32_e32 v27, 0xbfb8aa3b, v19
	v_exp_f32_e32 v26, v26
	v_exp_f32_e32 v27, v27
	v_add_f32_e32 v26, 1.0, v26
	v_add_f32_e32 v27, 1.0, v27
	v_rcp_f32_e32 v23, v26
	v_rcp_f32_e32 v19, v27
	v_mul_f32_e32 v26, 0xbfb8aa3b, v24
	v_mul_f32_e32 v27, 0xbfb8aa3b, v20
	v_exp_f32_e32 v26, v26
	v_exp_f32_e32 v27, v27
	v_add_f32_e32 v26, 1.0, v26
	v_add_f32_e32 v27, 1.0, v27
	v_rcp_f32_e32 v24, v26
	v_rcp_f32_e32 v20, v27
	v_mul_f32_e32 v26, 0xbfb8aa3b, v25
	v_mul_f32_e32 v27, 0xbfb8aa3b, v21
	v_exp_f32_e32 v26, v26
	v_exp_f32_e32 v27, v27
	v_add_f32_e32 v26, 1.0, v26
	v_add_f32_e32 v27, 1.0, v27
	v_rcp_f32_e32 v25, v26
	v_rcp_f32_e32 v21, v27
	s_branch .LBB0_326
.Lsg_14:
	v_mul_f32_e32 v18, 0xbfb8aa3b, v14
	v_mul_f32_e32 v19, 0xbfb8aa3b, v10
	v_exp_f32_e32 v18, v18
	v_exp_f32_e32 v19, v19
	v_add_f32_e32 v18, 1.0, v18
	v_add_f32_e32 v19, 1.0, v19
	v_rcp_f32_e32 v14, v18
	v_rcp_f32_e32 v10, v19
	v_mul_f32_e32 v18, 0xbfb8aa3b, v15
	v_mul_f32_e32 v19, 0xbfb8aa3b, v11
	v_exp_f32_e32 v18, v18
	v_exp_f32_e32 v19, v19
	v_add_f32_e32 v18, 1.0, v18
	v_add_f32_e32 v19, 1.0, v19
	v_rcp_f32_e32 v15, v18
	v_rcp_f32_e32 v11, v19
	v_mul_f32_e32 v18, 0xbfb8aa3b, v16
	v_mul_f32_e32 v19, 0xbfb8aa3b, v12
	v_exp_f32_e32 v18, v18
	v_exp_f32_e32 v19, v19
	v_add_f32_e32 v18, 1.0, v18
	v_add_f32_e32 v19, 1.0, v19
	v_rcp_f32_e32 v16, v18
	v_rcp_f32_e32 v12, v19
	v_mul_f32_e32 v18, 0xbfb8aa3b, v17
	v_mul_f32_e32 v19, 0xbfb8aa3b, v13
	v_exp_f32_e32 v18, v18
	v_exp_f32_e32 v19, v19
	v_add_f32_e32 v18, 1.0, v18
	v_add_f32_e32 v19, 1.0, v19
	v_rcp_f32_e32 v17, v18
	v_rcp_f32_e32 v13, v19
	s_branch .LBB0_328
.Lsg_15:
	v_mul_f32_e32 v10, 0xbfb8aa3b, v6
	v_mul_f32_e32 v11, 0xbfb8aa3b, v2
	v_exp_f32_e32 v10, v10
	v_exp_f32_e32 v11, v11
	v_add_f32_e32 v10, 1.0, v10
	v_add_f32_e32 v11, 1.0, v11
	v_rcp_f32_e32 v6, v10
	v_rcp_f32_e32 v2, v11
	v_mul_f32_e32 v10, 0xbfb8aa3b, v7
	v_mul_f32_e32 v11, 0xbfb8aa3b, v3
	v_exp_f32_e32 v10, v10
	v_exp_f32_e32 v11, v11
	v_add_f32_e32 v10, 1.0, v10
	v_add_f32_e32 v11, 1.0, v11
	v_rcp_f32_e32 v7, v10
	v_rcp_f32_e32 v3, v11
	v_mul_f32_e32 v10, 0xbfb8aa3b, v8
	v_mul_f32_e32 v11, 0xbfb8aa3b, v4
	v_exp_f32_e32 v10, v10
	v_exp_f32_e32 v11, v11
	v_add_f32_e32 v10, 1.0, v10
	v_add_f32_e32 v11, 1.0, v11
	v_rcp_f32_e32 v8, v10
	v_rcp_f32_e32 v4, v11
	v_mul_f32_e32 v10, 0xbfb8aa3b, v9
	v_mul_f32_e32 v11, 0xbfb8aa3b, v5
	v_exp_f32_e32 v10, v10
	v_exp_f32_e32 v11, v11
	v_add_f32_e32 v10, 1.0, v10
	v_add_f32_e32 v11, 1.0, v11
	v_rcp_f32_e32 v9, v10
	v_rcp_f32_e32 v5, v11
	s_branch .LBB0_330
